# GQA attention loop: replace over-draining vmcnt ladder by exact wait (vmcnt(4), or vmcnt(0) only when the second-half prefetch was skipped)
# speedup vs baseline: 1.0003x; 1.0003x over previous
; template <int D0> __device__ __forceinline__ void pv_one(f32x16& od, int vb, bf16x8 pa0, bf16x8 pa1, bf16x8 pa2, bf16x8 pa3) {
;   const s16x4 l0 = tr_read<v_rd_off(D0, 0, 0)>(vb), h0 = tr_read<v_rd_off(D0, 0, 1)>(vb), l1 = tr_read<v_rd_off(D0, 1, 0)>(vb), h1 = tr_read<v_rd_off(D0, 1, 1)>(vb);
;   const s16x4 l2 = tr_read<v_rd_off(D0, 2, 0)>(vb), h2 = tr_read<v_rd_off(D0, 2, 1)>(vb), l3 = tr_read<v_rd_off(D0, 3, 0)>(vb), h3 = tr_read<v_rd_off(D0, 3, 1)>(vb);
;   asm volatile("s_waitcnt lgkmcnt(0)" ::: "memory"); SBAR();
;     ...
;   od = __builtin_amdgcn_mfma_f32_32x32x16_bf16(pa0, PK(l0, h0), od, 0, 0, 0);
;   od = __builtin_amdgcn_mfma_f32_32x32x16_bf16(pa1, PK(l1, h1), od, 0, 0, 0);
;   od = __builtin_amdgcn_mfma_f32_32x32x16_bf16(pa2, PK(l2, h2), od, 0, 0, 0);
;   od = __builtin_amdgcn_mfma_f32_32x32x16_bf16(pa3, PK(l3, h3), od, 0, 0, 0);
;     ...
; }
; __device__ __forceinline__ void pv_d0(f32x16* o, int vb, bf16x8 pa0, bf16x8 pa1, bf16x8 pa2, bf16x8 pa3) {
;   pv_one<0>(o[0], vb, pa0, pa1, pa2, pa3); pv_one<1>(o[1], vb, pa0, pa1, pa2, pa3); pv_one<2>(o[2], vb, pa0, pa1, pa2, pa3); pv_one<3>(o[3], vb, pa0, pa1, pa2, pa3);
; }
; template <int DQK> __device__ __forceinline__ void pv_partialSM(f32x16* o, int vb, bf16x8 pa0, bf16x8 pa1, bf16x8 pa2, bf16x8 pa3,
;                                                                  f32x16& p0, f32x16& p1, float& m_reg, float& alpha) {
;   constexpr float SCALE = (DQK == 192) ? 0.07216878364870322f : (DQK == 64 ? 1.0f : 0.08838834764831845f);
;   constexpr float C = SCALE * 1.4426950408889634f;
;   pv_one<0>(o[0], vb, pa0, pa1, pa2, pa3);
;   float pmax = p0[0];
; #pragma unroll
;   for (int r = 1; r < 16; ++r) pmax = fmaxf(pmax, p0[r]);
;   pv_one<1>(o[1], vb, pa0, pa1, pa2, pa3);
; #pragma unroll
;   for (int r = 0; r < 16; ++r) pmax = fmaxf(pmax, p1[r]);
;   { auto rr = __builtin_amdgcn_permlane32_swap(__float_as_uint(pmax), __float_as_uint(pmax), false, false);
;     pmax = fmaxf(__uint_as_float(rr[0]), __uint_as_float(rr[1])); }
;   const bool keep = __all(pmax - m_reg <= THR / SCALE);
;   const float mn = keep ? m_reg : fmaxf(m_reg, pmax);
;   alpha = __builtin_amdgcn_exp2f((m_reg - mn) * C); m_reg = mn;
;   const float mnC = -mn * C;
;   pv_one<2>(o[2], vb, pa0, pa1, pa2, pa3);
; #pragma unroll
;   for (int r = 0; r < 16; ++r) { p0[r] = fmaf(p0[r], C, mnC); p1[r] = fmaf(p1[r], C, mnC); }
.LBB0_484:
	ds_read_b64_tr_b16 v[116:117], v216 offset:0
	ds_read_b64_tr_b16 v[118:119], v216 offset:0x800
	ds_read_b64_tr_b16 v[120:121], v216 offset:0x1000
	ds_read_b64_tr_b16 v[122:123], v216 offset:0x1800
	ds_read_b64_tr_b16 v[124:125], v216 offset:0x2000
	ds_read_b64_tr_b16 v[126:127], v216 offset:0x2800
	ds_read_b64_tr_b16 v[228:229], v216 offset:0x3000
	ds_read_b64_tr_b16 v[230:231], v216 offset:0x3800
	s_waitcnt lgkmcnt(0)
	s_nop 0
	v_mfma_f32_32x32x16_bf16 v[2:17], v[98:101], v[116:119], v[2:17]
	v_max_f32_e32 v116, v83, v83
	v_max_f32_e32 v117, v82, v82
	v_max_f32_e32 v116, v117, v116
	v_max3_f32 v116, v116, v84, v85
	v_max3_f32 v116, v116, v86, v87
	v_max3_f32 v116, v116, v88, v89
	v_max3_f32 v116, v116, v90, v91
	v_mfma_f32_32x32x16_bf16 v[2:17], v[102:105], v[120:123], v[2:17]
	v_max3_f32 v116, v116, v92, v93
	v_max3_f32 v116, v116, v94, v95
	v_max3_f32 v128, v116, v96, v97
	ds_read_b64_tr_b16 v[116:117], v216 offset:0x200
	ds_read_b64_tr_b16 v[118:119], v216 offset:0xa00
	ds_read_b64_tr_b16 v[120:121], v216 offset:0x1200
	ds_read_b64_tr_b16 v[122:123], v216 offset:0x1a00
	v_mfma_f32_32x32x16_bf16 v[2:17], v[106:109], v[124:127], v[2:17]
	ds_read_b64_tr_b16 v[124:125], v216 offset:0x2200
	ds_read_b64_tr_b16 v[126:127], v216 offset:0x2a00
	v_mfma_f32_32x32x16_bf16 v[2:17], v[110:113], v[228:231], v[2:17]
	ds_read_b64_tr_b16 v[228:229], v216 offset:0x3200
	ds_read_b64_tr_b16 v[230:231], v216 offset:0x3a00
	s_waitcnt lgkmcnt(0)
	v_mfma_f32_32x32x16_bf16 v[50:65], v[98:101], v[116:119], v[50:65]
	v_max3_f32 v128, v128, v66, v67
	v_max3_f32 v128, v128, v68, v69
	v_max3_f32 v128, v128, v70, v71
	v_max3_f32 v128, v128, v72, v73
	v_max3_f32 v128, v128, v74, v75
	v_max3_f32 v116, v128, v76, v77
	v_max3_f32 v116, v116, v78, v79
	v_mfma_f32_32x32x16_bf16 v[50:65], v[102:105], v[120:123], v[50:65]
	v_max3_f32 v116, v116, v80, v81
	v_mov_b32_e32 v117, v116
	s_nop 1
	v_permlane32_swap_b32_e32 v116, v117
	v_max_f32_e32 v117, v117, v117
	v_max_f32_e32 v116, v116, v116
	v_max_f32_e32 v116, v116, v117
	v_sub_f32_e32 v117, v116, v223
	v_cmp_ge_f32_e32 vcc, s22, v117
	s_cmp_eq_u64 vcc, exec
	v_max_f32_e32 v117, v223, v223
	v_mfma_f32_32x32x16_bf16 v[50:65], v[106:109], v[124:127], v[50:65]
	v_max_f32_e32 v116, v117, v116
	s_cselect_b64 vcc, -1, 0
	v_cndmask_b32_e32 v226, v116, v223, vcc
	v_sub_f32_e32 v116, v223, v226
	v_mul_f32_e32 v116, 0x3e0293ee, v116
	v_exp_f32_e32 v223, v116
	ds_read_b64_tr_b16 v[116:117], v216 offset:0x400
	ds_read_b64_tr_b16 v[118:119], v216 offset:0xc00
	ds_read_b64_tr_b16 v[120:121], v216 offset:0x1400
	v_mfma_f32_32x32x16_bf16 v[50:65], v[110:113], v[228:231], v[50:65]
	ds_read_b64_tr_b16 v[122:123], v216 offset:0x1c00
	ds_read_b64_tr_b16 v[124:125], v216 offset:0x2400
	ds_read_b64_tr_b16 v[126:127], v216 offset:0x2c00
	ds_read_b64_tr_b16 v[228:229], v216 offset:0x3400
	ds_read_b64_tr_b16 v[230:231], v216 offset:0x3c00
	s_waitcnt lgkmcnt(0)
	v_mul_f32_e32 v128, 0xbe0293ee, v226
	v_mfma_f32_32x32x16_bf16 v[34:49], v[98:101], v[116:119], v[34:49]
	v_fmamk_f32 v129, v94, 0x3e0293ee, v128
	v_fmamk_f32 v116, v82, 0x3e0293ee, v128
	v_fmamk_f32 v117, v83, 0x3e0293ee, v128
	v_fma_f32 v82, v66, s94, v128
	v_fma_f32 v83, v67, s94, v128
	ds_read_b64_tr_b16 v[66:67], v216 offset:0x600
	v_fmamk_f32 v118, v84, 0x3e0293ee, v128
	v_fmamk_f32 v119, v85, 0x3e0293ee, v128
	v_mfma_f32_32x32x16_bf16 v[34:49], v[102:105], v[120:123], v[34:49]
	v_fma_f32 v84, v68, s94, v128
	v_fma_f32 v85, v69, s94, v128
	ds_read_b64_tr_b16 v[68:69], v216 offset:0xe00
	v_fmamk_f32 v120, v86, 0x3e0293ee, v128
	v_fmamk_f32 v121, v87, 0x3e0293ee, v128
	v_fma_f32 v86, v70, s94, v128
	v_fma_f32 v87, v71, s94, v128
	ds_read_b64_tr_b16 v[70:71], v216 offset:0x1600
	v_fmamk_f32 v122, v88, 0x3e0293ee, v128
	v_mfma_f32_32x32x16_bf16 v[34:49], v[106:109], v[124:127], v[34:49]
	v_fmamk_f32 v123, v89, 0x3e0293ee, v128
	v_fma_f32 v88, v72, s94, v128
	v_fma_f32 v89, v73, s94, v128
	ds_read_b64_tr_b16 v[72:73], v216 offset:0x1e00
	v_fmamk_f32 v124, v90, 0x3e0293ee, v128
	v_fmamk_f32 v125, v91, 0x3e0293ee, v128
	v_pk_fma_f32 v[90:91], v[74:75], s[94:95], v[128:129] op_sel_hi:[1,0,0]
	ds_read_b64_tr_b16 v[74:75], v216 offset:0x2600
	v_mfma_f32_32x32x16_bf16 v[34:49], v[110:113], v[228:231], v[34:49]
	v_fmamk_f32 v126, v92, 0x3e0293ee, v128
	v_fmamk_f32 v127, v93, 0x3e0293ee, v128
	v_fma_f32 v92, v76, s94, v128
	v_fma_f32 v93, v77, s94, v128
	ds_read_b64_tr_b16 v[76:77], v216 offset:0x2e00
	v_fmamk_f32 v228, v95, 0x3e0293ee, v128
	v_mov_b32_e32 v230, v128
	v_pk_fma_f32 v[94:95], v[78:79], s[94:95], v[128:129] op_sel_hi:[1,0,0]
	ds_read_b64_tr_b16 v[78:79], v216 offset:0x3600
	v_fmamk_f32 v229, v96, 0x3e0293ee, v128
	v_fmac_f32_e32 v230, 0x3e0293ee, v97
	v_pk_fma_f32 v[96:97], v[80:81], s[94:95], v[128:129] op_sel_hi:[1,0,0]
	ds_read_b64_tr_b16 v[80:81], v216 offset:0x3e00
	s_waitcnt lgkmcnt(0)
	v_mfma_f32_32x32x16_bf16 v[18:33], v[98:101], v[66:69], v[18:33]
	v_exp_f32_e32 v66, v116
	v_exp_f32_e32 v67, v117
	v_exp_f32_e32 v68, v118
	v_exp_f32_e32 v69, v119
	v_mfma_f32_32x32x16_bf16 v[18:33], v[102:105], v[70:73], v[18:33]
	v_exp_f32_e32 v70, v120
	v_exp_f32_e32 v71, v121
	v_exp_f32_e32 v72, v122
	v_exp_f32_e32 v73, v123
	v_mfma_f32_32x32x16_bf16 v[18:33], v[106:109], v[74:77], v[18:33]
	v_exp_f32_e32 v74, v124
	v_exp_f32_e32 v75, v125
	v_exp_f32_e32 v76, v126
	v_exp_f32_e32 v77, v127
	v_mfma_f32_32x32x16_bf16 v[18:33], v[110:113], v[78:81], v[18:33]
	v_exp_f32_e32 v78, v129
	v_exp_f32_e32 v79, v228
	v_exp_f32_e32 v80, v229
	v_exp_f32_e32 v81, v230
	s_barrier
	s_waitcnt vmcnt(4)
	v_cmp_gt_f32_e32 vcc, 1.0, v223
	s_cmp_ge_u32 s16, s15
	s_cbranch_scc0 .Lgqa_w1
	s_waitcnt vmcnt(0)
.Lgqa_w1:
	ds_write_b128 v219, v[178:181] offset:16384
	ds_write_b128 v220, v[190:193] offset:16384
	ds_write_b128 v221, v[182:185] offset:50176
	ds_write_b128 v221, v[186:189] offset:58880
	s_cbranch_vccz .LBB0_488
	s_and_saveexec_b64 s[4:5], s[40:41]
	ds_write_b32 v214, v223 offset:128
	s_or_b64 exec, exec, s[4:5]
	s_waitcnt lgkmcnt(0)
	v_add_u32_e32 v110, s14, v0
	ds_read_b128 v[98:101], v110 offset:224
	ds_read_b128 v[102:105], v110 offset:192
	ds_read_b128 v[106:109], v110 offset:160
	ds_read_b128 v[110:113], v110 offset:128
	s_waitcnt lgkmcnt(3)
	v_pk_mul_f32 v[14:15], v[14:15], v[98:99]
	s_waitcnt lgkmcnt(2)
	v_pk_mul_f32 v[10:11], v[10:11], v[102:103]
	s_waitcnt lgkmcnt(1)
	v_pk_mul_f32 v[6:7], v[6:7], v[106:107]
	v_pk_mul_f32 v[16:17], v[16:17], v[100:101]
	v_pk_mul_f32 v[12:13], v[12:13], v[104:105]
	v_pk_mul_f32 v[8:9], v[8:9], v[108:109]
	s_waitcnt lgkmcnt(0)
	v_pk_mul_f32 v[4:5], v[4:5], v[112:113]
	v_pk_mul_f32 v[2:3], v[2:3], v[110:111]
	v_pk_mul_f32 v[62:63], v[62:63], v[98:99]
	v_pk_mul_f32 v[58:59], v[58:59], v[102:103]
	v_pk_mul_f32 v[54:55], v[54:55], v[106:107]
	v_pk_mul_f32 v[64:65], v[64:65], v[100:101]
	v_pk_mul_f32 v[60:61], v[60:61], v[104:105]
	v_pk_mul_f32 v[56:57], v[56:57], v[108:109]
	v_pk_mul_f32 v[52:53], v[52:53], v[112:113]
	v_pk_mul_f32 v[50:51], v[50:51], v[110:111]
	v_pk_mul_f32 v[46:47], v[46:47], v[98:99]
	v_pk_mul_f32 v[42:43], v[42:43], v[102:103]
	v_pk_mul_f32 v[38:39], v[38:39], v[106:107]
	v_pk_mul_f32 v[48:49], v[48:49], v[100:101]
	v_pk_mul_f32 v[44:45], v[44:45], v[104:105]
	v_pk_mul_f32 v[40:41], v[40:41], v[108:109]
	v_pk_mul_f32 v[36:37], v[36:37], v[112:113]
	v_pk_mul_f32 v[34:35], v[34:35], v[110:111]
	v_pk_mul_f32 v[30:31], v[30:31], v[98:99]
	v_pk_mul_f32 v[26:27], v[26:27], v[102:103]
	v_pk_mul_f32 v[22:23], v[22:23], v[106:107]
	v_pk_mul_f32 v[32:33], v[32:33], v[100:101]
	v_pk_mul_f32 v[28:29], v[28:29], v[104:105]
	v_pk_mul_f32 v[24:25], v[24:25], v[108:109]
	v_pk_mul_f32 v[20:21], v[20:21], v[112:113]
	v_pk_mul_f32 v[18:19], v[18:19], v[110:111]
